# plus third of phase-7 own conversion loops reversed (SWA-half item balance 33/33)
# baseline (speedup 1.0000x reference)
; __device__ __forceinline__ void conv_matrix(const float* W, int K, int N, const float* gain, bf16_t* WT, int Kd, int mode, int row_off, LAS float* scr, int lane, int gw, int NGW) {
;     ...
;     for (int it = gw; it < items; it += NGW) {
;         const int kb = it / nblk, nb = it % nblk, k0 = 64 * kb, n0 = 32 * nb;
;         float wv[32];
; #pragma unroll
;         for (int i = 0; i < 32; ++i) wv[i] = W[(size_t)(k0 + 2 * i + (lane >> 5)) * N + n0 + (lane & 31)];
.LBB0_723:
	s_ashr_i32 s0, s5, 31
	s_lshr_b32 s0, s0, 26
	s_add_i32 s0, s5, s0
	s_ashr_i32 s18, s0, 6
	s_andn2_b32 s0, s0, 63
	s_lshl_b32 s1, s18, 11
	s_sub_i32 s22, s4, s1
	v_or_b32_e32 v12, s0, v114
	s_ashr_i32 s23, s22, 31
	v_ashrrev_i32_e32 v13, 31, v12
	v_lshl_add_u64 v[10:11], s[22:23], 2, v[2:3]
	v_lshlrev_b64 v[14:15], 13, v[12:13]
	v_lshl_add_u64 v[14:15], v[10:11], 0, v[14:15]
	flat_load_dword v9, v[14:15]
	v_or_b32_e32 v14, 2, v12
	v_or_b32_e32 v16, 4, v12
	v_ashrrev_i32_e32 v15, 31, v14
	v_ashrrev_i32_e32 v17, 31, v16
	v_lshlrev_b64 v[14:15], 13, v[14:15]
	v_lshlrev_b64 v[16:17], 13, v[16:17]
	v_lshl_add_u64 v[14:15], v[10:11], 0, v[14:15]
	v_lshl_add_u64 v[16:17], v[10:11], 0, v[16:17]
	flat_load_dword v14, v[14:15]
	v_or_b32_e32 v18, 8, v12
	flat_load_dword v15, v[16:17]
	v_or_b32_e32 v16, 6, v12
	v_ashrrev_i32_e32 v17, 31, v16
	v_ashrrev_i32_e32 v19, 31, v18
	v_lshlrev_b64 v[16:17], 13, v[16:17]
	v_lshlrev_b64 v[18:19], 13, v[18:19]
	v_lshl_add_u64 v[16:17], v[10:11], 0, v[16:17]
	v_lshl_add_u64 v[18:19], v[10:11], 0, v[18:19]
	flat_load_dword v16, v[16:17]
	v_or_b32_e32 v20, 12, v12
	flat_load_dword v17, v[18:19]
	v_or_b32_e32 v18, 10, v12
	v_ashrrev_i32_e32 v19, 31, v18
	v_ashrrev_i32_e32 v21, 31, v20
	v_lshlrev_b64 v[18:19], 13, v[18:19]
	v_lshlrev_b64 v[20:21], 13, v[20:21]
	v_lshl_add_u64 v[18:19], v[10:11], 0, v[18:19]
	v_lshl_add_u64 v[20:21], v[10:11], 0, v[20:21]
	flat_load_dword v18, v[18:19]
	v_or_b32_e32 v22, 16, v12
	flat_load_dword v19, v[20:21]
	v_or_b32_e32 v20, 14, v12
	v_ashrrev_i32_e32 v21, 31, v20
	v_ashrrev_i32_e32 v23, 31, v22
	v_lshlrev_b64 v[20:21], 13, v[20:21]
	v_lshlrev_b64 v[22:23], 13, v[22:23]
	v_lshl_add_u64 v[20:21], v[10:11], 0, v[20:21]
	v_lshl_add_u64 v[22:23], v[10:11], 0, v[22:23]
	flat_load_dword v20, v[20:21]
	v_or_b32_e32 v24, 20, v12
	flat_load_dword v21, v[22:23]
	v_or_b32_e32 v22, 18, v12
	v_ashrrev_i32_e32 v23, 31, v22
	v_ashrrev_i32_e32 v25, 31, v24
	v_lshlrev_b64 v[22:23], 13, v[22:23]
	v_lshlrev_b64 v[24:25], 13, v[24:25]
	v_lshl_add_u64 v[22:23], v[10:11], 0, v[22:23]
	v_lshl_add_u64 v[24:25], v[10:11], 0, v[24:25]
	flat_load_dword v22, v[22:23]
	v_or_b32_e32 v26, 24, v12
	flat_load_dword v23, v[24:25]
	v_or_b32_e32 v24, 22, v12
	v_ashrrev_i32_e32 v25, 31, v24
	v_ashrrev_i32_e32 v27, 31, v26
	v_lshlrev_b64 v[24:25], 13, v[24:25]
	v_lshlrev_b64 v[26:27], 13, v[26:27]
	v_lshl_add_u64 v[24:25], v[10:11], 0, v[24:25]
	v_lshl_add_u64 v[26:27], v[10:11], 0, v[26:27]
	flat_load_dword v24, v[24:25]
	v_or_b32_e32 v28, 28, v12
	flat_load_dword v25, v[26:27]
	v_or_b32_e32 v26, 26, v12
	v_ashrrev_i32_e32 v27, 31, v26
	v_ashrrev_i32_e32 v29, 31, v28
	v_lshlrev_b64 v[26:27], 13, v[26:27]
	v_lshlrev_b64 v[28:29], 13, v[28:29]
	v_lshl_add_u64 v[26:27], v[10:11], 0, v[26:27]
	v_lshl_add_u64 v[28:29], v[10:11], 0, v[28:29]
	flat_load_dword v26, v[26:27]
	v_or_b32_e32 v30, 32, v12
	flat_load_dword v27, v[28:29]
	v_or_b32_e32 v28, 30, v12
	v_ashrrev_i32_e32 v29, 31, v28
	v_ashrrev_i32_e32 v31, 31, v30
	v_lshlrev_b64 v[28:29], 13, v[28:29]
	v_lshlrev_b64 v[30:31], 13, v[30:31]
	v_lshl_add_u64 v[28:29], v[10:11], 0, v[28:29]
	v_lshl_add_u64 v[30:31], v[10:11], 0, v[30:31]
	flat_load_dword v28, v[28:29]
	v_or_b32_e32 v32, 36, v12
	flat_load_dword v29, v[30:31]
	v_or_b32_e32 v30, 34, v12
	v_ashrrev_i32_e32 v31, 31, v30
	v_ashrrev_i32_e32 v33, 31, v32
	v_lshlrev_b64 v[30:31], 13, v[30:31]
	v_lshlrev_b64 v[32:33], 13, v[32:33]
	v_lshl_add_u64 v[30:31], v[10:11], 0, v[30:31]
	v_lshl_add_u64 v[32:33], v[10:11], 0, v[32:33]
	flat_load_dword v30, v[30:31]
	v_or_b32_e32 v34, 40, v12
	flat_load_dword v31, v[32:33]
	v_or_b32_e32 v32, 38, v12
	v_ashrrev_i32_e32 v33, 31, v32
	v_ashrrev_i32_e32 v35, 31, v34
	v_lshlrev_b64 v[32:33], 13, v[32:33]
	v_lshlrev_b64 v[34:35], 13, v[34:35]
	v_lshl_add_u64 v[32:33], v[10:11], 0, v[32:33]
	v_lshl_add_u64 v[34:35], v[10:11], 0, v[34:35]
	flat_load_dword v32, v[32:33]
	v_or_b32_e32 v36, 44, v12
	flat_load_dword v33, v[34:35]
	v_or_b32_e32 v34, 42, v12
	v_ashrrev_i32_e32 v35, 31, v34
	v_ashrrev_i32_e32 v37, 31, v36
	v_lshlrev_b64 v[34:35], 13, v[34:35]
	v_lshlrev_b64 v[36:37], 13, v[36:37]
	v_lshl_add_u64 v[34:35], v[10:11], 0, v[34:35]
	v_lshl_add_u64 v[36:37], v[10:11], 0, v[36:37]
	flat_load_dword v34, v[34:35]
	v_or_b32_e32 v38, 48, v12
	flat_load_dword v35, v[36:37]
	v_or_b32_e32 v36, 46, v12
	v_ashrrev_i32_e32 v37, 31, v36
	v_ashrrev_i32_e32 v39, 31, v38
	v_lshlrev_b64 v[36:37], 13, v[36:37]
	v_lshlrev_b64 v[38:39], 13, v[38:39]
	v_lshl_add_u64 v[36:37], v[10:11], 0, v[36:37]
	v_lshl_add_u64 v[38:39], v[10:11], 0, v[38:39]
	flat_load_dword v36, v[36:37]
	v_or_b32_e32 v40, 52, v12
	flat_load_dword v37, v[38:39]
	v_or_b32_e32 v38, 50, v12
	v_ashrrev_i32_e32 v39, 31, v38
	v_ashrrev_i32_e32 v41, 31, v40
	v_lshlrev_b64 v[38:39], 13, v[38:39]
	v_lshlrev_b64 v[40:41], 13, v[40:41]
	v_lshl_add_u64 v[38:39], v[10:11], 0, v[38:39]
	v_lshl_add_u64 v[40:41], v[10:11], 0, v[40:41]
	flat_load_dword v38, v[38:39]
	v_or_b32_e32 v42, 56, v12
	flat_load_dword v39, v[40:41]
	v_or_b32_e32 v40, 54, v12
	v_ashrrev_i32_e32 v41, 31, v40
	v_ashrrev_i32_e32 v43, 31, v42
	v_lshlrev_b64 v[40:41], 13, v[40:41]
	v_lshlrev_b64 v[42:43], 13, v[42:43]
	v_lshl_add_u64 v[40:41], v[10:11], 0, v[40:41]
	v_lshl_add_u64 v[42:43], v[10:11], 0, v[42:43]
	flat_load_dword v40, v[40:41]
	v_or_b32_e32 v44, 60, v12
	flat_load_dword v41, v[42:43]
	v_or_b32_e32 v42, 58, v12
	v_ashrrev_i32_e32 v43, 31, v42
	v_or_b32_e32 v12, 62, v12
	v_lshlrev_b64 v[42:43], 13, v[42:43]
	v_ashrrev_i32_e32 v45, 31, v44
	v_ashrrev_i32_e32 v13, 31, v12
	v_lshl_add_u64 v[42:43], v[10:11], 0, v[42:43]
	v_lshlrev_b64 v[44:45], 13, v[44:45]
	v_lshlrev_b64 v[12:13], 13, v[12:13]
	flat_load_dword v42, v[42:43]
	v_lshl_add_u64 v[44:45], v[10:11], 0, v[44:45]
	v_lshl_add_u64 v[10:11], v[10:11], 0, v[12:13]
	flat_load_dword v10, v[10:11]
	s_mul_i32 s18, s18, 0xff500000
	flat_load_dword v43, v[44:45]
	s_waitcnt vmcnt(0) lgkmcnt(0)
; __device__ __forceinline__ unsigned cvt_pk_bf16(float lo, float hi) { f32x2 v = {lo, hi}; bf16x2_t b = __builtin_convertvector(v, bf16x2_t); return __builtin_bit_cast(unsigned, b); }
; #define LAS __attribute__((address_space(3)))
; __device__ __forceinline__ void conv_matrix(const float* W, int K, int N, const float* gain, bf16_t* WT, int Kd, int mode, int row_off, LAS float* scr, int lane, int gw, int NGW) {
;     ...
;     for (int it = gw; it < items; it += NGW) {
;         const int kb = it / nblk, nb = it % nblk, k0 = 64 * kb, n0 = 32 * nb;
;     ...
; #pragma unroll
;         for (int i = 0; i < 32; ++i) scr[(2 * i + (lane >> 5)) * 33 + (lane & 31)] = wv[i];
;         asm volatile("s_waitcnt lgkmcnt(0)" ::: "memory");
;         const int c = lane & 7;
;         const int rbase = mode == 0 ? row_off + n0 : ((n0 >> 7) * 256 + (n0 & 127) + (mode == 2 ? 128 : 0));
; #pragma unroll
;         for (int j = 0; j < 4; ++j) { const int n = (lane >> 3) + 8 * j; const LAS float* s = scr + (8 * c) * 33 + n;
;             u32x4 o; o.x = cvt_pk_bf16(s[0 * 33], s[1 * 33]); o.y = cvt_pk_bf16(s[2 * 33], s[3 * 33]); o.z = cvt_pk_bf16(s[4 * 33], s[5 * 33]); o.w = cvt_pk_bf16(s[6 * 33], s[7 * 33]);
;             *(u32x4*)(WT + (size_t)(rbase + n) * Kd + k0 + 8 * c) = o; }
;         asm volatile("s_waitcnt lgkmcnt(0)" ::: "memory");
;     }
	ds_write2_b32 v116, v9, v14 offset1:66
	ds_write2_b32 v116, v15, v16 offset0:132 offset1:198
	ds_write2_b32 v117, v17, v18 offset0:8 offset1:74
	ds_write2_b32 v117, v19, v20 offset0:140 offset1:206
	ds_write2_b32 v118, v21, v22 offset0:16 offset1:82
	ds_write2_b32 v118, v23, v24 offset0:148 offset1:214
	ds_write2_b32 v119, v25, v26 offset0:24 offset1:90
	ds_write2_b32 v119, v27, v28 offset0:156 offset1:222
	ds_write2_b32 v120, v29, v30 offset0:32 offset1:98
	ds_write2_b32 v120, v31, v32 offset0:164 offset1:230
	ds_write2_b32 v121, v33, v34 offset0:40 offset1:106
	ds_write2_b32 v121, v35, v36 offset0:172 offset1:238
	ds_write2_b32 v122, v37, v38 offset0:48 offset1:114
	ds_write2_b32 v122, v39, v40 offset0:180 offset1:246
	ds_write2_b32 v123, v41, v42 offset0:56 offset1:122
	ds_write2_b32 v123, v43, v10 offset0:188 offset1:254
	s_waitcnt lgkmcnt(0)
	ds_read_b32 v9, v115
	ds_read_b32 v10, v115 offset:132
	s_ashr_i32 s1, s0, 31
	v_add_u32_e32 v16, s18, v7
	v_lshl_add_u64 v[14:15], s[0:1], 1, v[4:5]
	v_ashrrev_i32_e32 v17, 31, v16
	s_waitcnt lgkmcnt(0)
	v_cvt_pk_bf16_f32 v10, v9, v10
	ds_read_b32 v9, v115 offset:264
	ds_read_b32 v11, v115 offset:396
	v_lshl_add_u64 v[18:19], v[16:17], 1, v[14:15]
	s_add_i32 s5, s5, s8
	s_add_i32 s4, s4, s10
	v_add_u32_e32 v7, s12, v7
	s_waitcnt lgkmcnt(0)
	v_cvt_pk_bf16_f32 v11, v9, v11
	ds_read_b32 v9, v115 offset:528
	ds_read_b32 v12, v115 offset:660
	s_cmpk_lt_i32 s5, 0x1600
	s_waitcnt lgkmcnt(0)
	v_cvt_pk_bf16_f32 v12, v9, v12
	ds_read_b32 v9, v115 offset:792
	ds_read_b32 v13, v115 offset:924
	s_waitcnt lgkmcnt(0)
	v_cvt_pk_bf16_f32 v13, v9, v13
	flat_store_dwordx4 v[18:19], v[10:13]
	ds_read_b32 v9, v115 offset:32
	ds_read_b32 v10, v115 offset:164
	v_add_u32_e32 v18, 0xb000, v16
	v_ashrrev_i32_e32 v19, 31, v18
	v_lshl_add_u64 v[18:19], v[18:19], 1, v[14:15]
	s_waitcnt lgkmcnt(0)
	v_cvt_pk_bf16_f32 v10, v9, v10
	ds_read_b32 v9, v115 offset:296
	ds_read_b32 v11, v115 offset:428
	s_waitcnt lgkmcnt(0)
	v_cvt_pk_bf16_f32 v11, v9, v11
	ds_read_b32 v9, v115 offset:560
	ds_read_b32 v12, v115 offset:692
	s_waitcnt lgkmcnt(0)
	v_cvt_pk_bf16_f32 v12, v9, v12
	ds_read_b32 v9, v115 offset:824
	ds_read_b32 v13, v115 offset:956
	s_waitcnt lgkmcnt(0)
	v_cvt_pk_bf16_f32 v13, v9, v13
	flat_store_dwordx4 v[18:19], v[10:13]
	ds_read_b32 v9, v115 offset:64
	ds_read_b32 v10, v115 offset:196
	v_add_u32_e32 v18, 0x16000, v16
	v_ashrrev_i32_e32 v19, 31, v18
	v_lshl_add_u64 v[18:19], v[18:19], 1, v[14:15]
	v_add_u32_e32 v16, 0x21000, v16
	s_waitcnt lgkmcnt(0)
	v_cvt_pk_bf16_f32 v10, v9, v10
	ds_read_b32 v9, v115 offset:328
	ds_read_b32 v11, v115 offset:460
	v_ashrrev_i32_e32 v17, 31, v16
	v_lshl_add_u64 v[14:15], v[16:17], 1, v[14:15]
	s_waitcnt lgkmcnt(0)
	v_cvt_pk_bf16_f32 v11, v9, v11
	ds_read_b32 v9, v115 offset:592
	ds_read_b32 v12, v115 offset:724
	s_waitcnt lgkmcnt(0)
	v_cvt_pk_bf16_f32 v12, v9, v12
	ds_read_b32 v9, v115 offset:856
	ds_read_b32 v13, v115 offset:988
	s_waitcnt lgkmcnt(0)
	v_cvt_pk_bf16_f32 v13, v9, v13
	flat_store_dwordx4 v[18:19], v[10:13]
	ds_read_b32 v9, v115 offset:96
	ds_read_b32 v10, v115 offset:228
	s_waitcnt lgkmcnt(0)
	v_cvt_pk_bf16_f32 v10, v9, v10
	ds_read_b32 v9, v115 offset:360
	ds_read_b32 v11, v115 offset:492
	s_waitcnt lgkmcnt(0)
	v_cvt_pk_bf16_f32 v11, v9, v11
	ds_read_b32 v9, v115 offset:624
	ds_read_b32 v12, v115 offset:756
	s_waitcnt lgkmcnt(0)
	v_cvt_pk_bf16_f32 v12, v9, v12
	ds_read_b32 v9, v115 offset:888
	ds_read_b32 v13, v115 offset:1020
	s_waitcnt lgkmcnt(0)
	v_cvt_pk_bf16_f32 v13, v9, v13
	flat_store_dwordx4 v[14:15], v[10:13]
	s_waitcnt lgkmcnt(0)
	s_cbranch_scc1 .LBB0_723
	v_readlane_b32 s0, v254, 6
	v_mov_b32_e32 v9, v0
	s_sub_i32 s22, s8, s2
	s_add_i32 s22, s22, -1
	s_lshl_b32 s18, s22, 6
	v_mov_b32_e32 v2, s0
	v_readlane_b32 s0, v254, 7
	ds_read_b128 v[14:17], v2
	s_lshl_b32 s19, s22, 5
	v_mov_b32_e32 v2, s0
	v_readlane_b32 s0, v254, 4
	s_waitcnt lgkmcnt(0)
	v_cmp_ne_u64_e64 s[40:41], 0, v[14:15]
	v_mov_b32_e32 v7, s0
	ds_read_b128 v[2:5], v2
	ds_read_b64 v[10:11], v7
	s_mov_b64 s[0:1], 0x2000
	v_mov_b32_e32 v7, v0
	v_lshl_add_u64 v[12:13], v[14:15], 0, s[0:1]
	v_lshl_add_u64 v[16:17], v[16:17], 0, v[6:7]
	s_mov_b64 s[0:1], 0x2c00000
	v_lshl_add_u64 v[16:17], v[16:17], 0, s[0:1]
	s_waitcnt lgkmcnt(0)
	v_lshl_add_u64 v[14:15], v[10:11], 0, v[8:9]
	s_mov_b64 s[0:1], 0x29300000
	v_lshl_add_u64 v[14:15], v[14:15], 0, s[0:1]
	s_branch .LBB0_726
